# v19 plus strength-reduced row-B bias pointer in B-attention chunk and v_mov_b64 accumulator zeroing in the five GEMM tile loops
# baseline (speedup 1.0000x reference)
; template <class Epi>
; DI void gemm_phase(PG8_LAS unsigned char* lds, const Gemm g, const StaticOrder& S, const Epi& E) {
;     ...
;     const bool has_next = S.next(ui + 1, nxt);
;     const char* nA = has_next ? (const char*)g.A + (size_t)nxt.pm * tstepA : cA; const char* nB = has_next ? (const char*)g.Bt + (size_t)nxt.pn * tstepB : cB;
;     ...
; #pragma unroll
;     for (int a = 0; a < 2; ++a)
; #pragma unroll
;       for (int b = 0; b < 2; ++b)
; #pragma unroll
;         for (int m = 0; m < 4; ++m)
; #pragma unroll
;           for (int n = 0; n < 2; ++n) acc[a][b][m][n] = (f32x4){0.f, 0.f, 0.f, 0.f};
;     cur = nxt; cA = nA; cB = nB; ++ui;
.LBB0_115:
	s_ashr_i32 s15, s14, 31
	s_lshl_b64 s[18:19], s[14:15], 19
	s_add_u32 s18, s35, s18
	s_addc_u32 s19, s72, s19
	s_and_b64 s[0:1], s[0:1], exec
	s_cselect_b32 s15, s19, s71
	s_cselect_b32 s93, s18, s70
	s_add_u32 s0, s12, 0x80
	s_addc_u32 s1, s13, 0
	s_add_u32 s94, s70, 0x100
	v_mov_b32_e32 v2, 0
	v_lshl_add_u64 v[140:141], s[0:1], 0, v[136:137]
	v_lshl_add_u64 v[148:149], s[0:1], 0, v[138:139]
	s_addc_u32 s97, s71, 0
	s_mov_b32 vcc_lo, -2
	s_mov_b64 s[0:1], 0
	v_mov_b32_e32 v3, v2
	v_mov_b64_e32 v[4:5], v[2:3]
	v_mov_b64_e32 v[6:7], v[2:3]
	v_mov_b64_e32 v[8:9], v[2:3]
	v_mov_b64_e32 v[10:11], v[2:3]
	v_mov_b64_e32 v[12:13], v[2:3]
	v_mov_b64_e32 v[14:15], v[2:3]
	v_mov_b64_e32 v[16:17], v[2:3]
	v_mov_b64_e32 v[26:27], v[2:3]
	v_mov_b64_e32 v[28:29], v[2:3]
	v_mov_b64_e32 v[30:31], v[2:3]
	v_mov_b64_e32 v[32:33], v[2:3]
	v_mov_b64_e32 v[42:43], v[2:3]
	v_mov_b64_e32 v[44:45], v[2:3]
	v_mov_b64_e32 v[46:47], v[2:3]
	v_mov_b64_e32 v[48:49], v[2:3]
	v_mov_b64_e32 v[18:19], v[2:3]
	v_mov_b64_e32 v[20:21], v[2:3]
	v_mov_b64_e32 v[22:23], v[2:3]
	v_mov_b64_e32 v[24:25], v[2:3]
	v_mov_b64_e32 v[34:35], v[2:3]
	v_mov_b64_e32 v[36:37], v[2:3]
	v_mov_b64_e32 v[38:39], v[2:3]
	v_mov_b64_e32 v[40:41], v[2:3]
	v_mov_b64_e32 v[50:51], v[2:3]
	v_mov_b64_e32 v[52:53], v[2:3]
	v_mov_b64_e32 v[54:55], v[2:3]
	v_mov_b64_e32 v[56:57], v[2:3]
	v_mov_b64_e32 v[58:59], v[2:3]
	v_mov_b64_e32 v[60:61], v[2:3]
	v_mov_b64_e32 v[62:63], v[2:3]
	v_mov_b64_e32 v[64:65], v[2:3]
	v_mov_b64_e32 v[66:67], v[2:3]
	v_mov_b64_e32 v[68:69], v[2:3]
	v_mov_b64_e32 v[70:71], v[2:3]
	v_mov_b64_e32 v[72:73], v[2:3]
	v_mov_b64_e32 v[74:75], v[2:3]
	v_mov_b64_e32 v[76:77], v[2:3]
	v_mov_b64_e32 v[78:79], v[2:3]
	v_mov_b64_e32 v[80:81], v[2:3]
	v_mov_b64_e32 v[90:91], v[2:3]
	v_mov_b64_e32 v[92:93], v[2:3]
	v_mov_b64_e32 v[94:95], v[2:3]
	v_mov_b64_e32 v[96:97], v[2:3]
	v_mov_b64_e32 v[106:107], v[2:3]
	v_mov_b64_e32 v[108:109], v[2:3]
	v_mov_b64_e32 v[110:111], v[2:3]
	v_mov_b64_e32 v[112:113], v[2:3]
	v_mov_b64_e32 v[82:83], v[2:3]
	v_mov_b64_e32 v[84:85], v[2:3]
	v_mov_b64_e32 v[86:87], v[2:3]
	v_mov_b64_e32 v[88:89], v[2:3]
	v_mov_b64_e32 v[98:99], v[2:3]
	v_mov_b64_e32 v[100:101], v[2:3]
	v_mov_b64_e32 v[102:103], v[2:3]
	v_mov_b64_e32 v[104:105], v[2:3]
	v_mov_b64_e32 v[114:115], v[2:3]
	v_mov_b64_e32 v[116:117], v[2:3]
	v_mov_b64_e32 v[118:119], v[2:3]
	v_mov_b64_e32 v[120:121], v[2:3]
	v_mov_b64_e32 v[122:123], v[2:3]
	v_mov_b64_e32 v[124:125], v[2:3]
	v_mov_b64_e32 v[126:127], v[2:3]
	v_mov_b64_e32 v[128:129], v[2:3]

; template <class Epi>
; DI void gemm_phase(PG8_LAS unsigned char* lds, const Gemm g, const StaticOrder& S, const Epi& E) {
;     ...
;     const bool has_next = S.next(ui + 1, nxt);
;     const char* nA = has_next ? (const char*)g.A + (size_t)nxt.pm * tstepA : cA; const char* nB = has_next ? (const char*)g.Bt + (size_t)nxt.pn * tstepB : cB;
;     ...
; #pragma unroll
;     for (int a = 0; a < 2; ++a)
; #pragma unroll
;       for (int b = 0; b < 2; ++b)
; #pragma unroll
;         for (int m = 0; m < 4; ++m)
; #pragma unroll
;           for (int n = 0; n < 2; ++n) acc[a][b][m][n] = (f32x4){0.f, 0.f, 0.f, 0.f};
;     cur = nxt; cA = nA; cB = nB; ++ui;
.LBB0_219:
	v_mov_b64_e32 v[2:3], 0x1000
	s_ashr_i32 s13, s12, 31
	v_cmp_lt_i64_e32 vcc, s[14:15], v[2:3]
	s_lshl_b64 s[14:15], s[12:13], 19
	s_add_u32 s14, s36, s14
	s_addc_u32 s15, s37, s15
	s_and_b64 s[16:17], vcc, exec
	s_cselect_b32 s13, s15, s9
	s_cselect_b32 s21, s14, s8
	s_ashr_i32 s1, s0, 31
	s_lshl_b64 s[16:17], s[0:1], 19
	s_add_u32 s16, s69, s16
	s_addc_u32 s17, s93, s17
	s_and_b64 s[18:19], vcc, exec
	s_cselect_b32 s1, s17, s11
	s_cselect_b32 s22, s16, s10
	s_add_u32 s8, s8, 0x40080
	s_addc_u32 s9, s9, 0
	s_add_u32 s23, s10, 0x100
	v_mov_b32_e32 v2, 0
	s_addc_u32 s24, s11, 0
	s_mov_b32 s25, -2
	v_mov_b32_e32 v3, v2
	v_mov_b64_e32 v[4:5], v[2:3]
	v_mov_b64_e32 v[6:7], v[2:3]
	v_mov_b64_e32 v[8:9], v[2:3]
	v_mov_b64_e32 v[18:19], v[2:3]
	v_mov_b64_e32 v[20:21], v[2:3]
	v_mov_b64_e32 v[22:23], v[2:3]
	v_mov_b64_e32 v[24:25], v[2:3]
	v_mov_b64_e32 v[34:35], v[2:3]
	v_mov_b64_e32 v[36:37], v[2:3]
	v_mov_b64_e32 v[38:39], v[2:3]
	v_mov_b64_e32 v[40:41], v[2:3]
	v_mov_b64_e32 v[50:51], v[2:3]
	v_mov_b64_e32 v[52:53], v[2:3]
	v_mov_b64_e32 v[54:55], v[2:3]
	v_mov_b64_e32 v[56:57], v[2:3]
	v_mov_b64_e32 v[10:11], v[2:3]
	v_mov_b64_e32 v[12:13], v[2:3]
	v_mov_b64_e32 v[14:15], v[2:3]
	v_mov_b64_e32 v[16:17], v[2:3]
	v_mov_b64_e32 v[26:27], v[2:3]
	v_mov_b64_e32 v[28:29], v[2:3]
	v_mov_b64_e32 v[30:31], v[2:3]
	v_mov_b64_e32 v[32:33], v[2:3]
	v_mov_b64_e32 v[42:43], v[2:3]
	v_mov_b64_e32 v[44:45], v[2:3]
	v_mov_b64_e32 v[46:47], v[2:3]
	v_mov_b64_e32 v[48:49], v[2:3]
	v_mov_b64_e32 v[58:59], v[2:3]
	v_mov_b64_e32 v[60:61], v[2:3]
	v_mov_b64_e32 v[62:63], v[2:3]
	v_mov_b64_e32 v[64:65], v[2:3]
	v_mov_b64_e32 v[66:67], v[2:3]
	v_mov_b64_e32 v[68:69], v[2:3]
	v_mov_b64_e32 v[70:71], v[2:3]
	v_mov_b64_e32 v[72:73], v[2:3]
	v_mov_b64_e32 v[82:83], v[2:3]
	v_mov_b64_e32 v[84:85], v[2:3]
	v_mov_b64_e32 v[86:87], v[2:3]
	v_mov_b64_e32 v[88:89], v[2:3]
	v_mov_b64_e32 v[98:99], v[2:3]
	v_mov_b64_e32 v[100:101], v[2:3]
	v_mov_b64_e32 v[102:103], v[2:3]
	v_mov_b64_e32 v[104:105], v[2:3]
	v_mov_b64_e32 v[114:115], v[2:3]
	v_mov_b64_e32 v[116:117], v[2:3]
	v_mov_b64_e32 v[118:119], v[2:3]
	v_mov_b64_e32 v[120:121], v[2:3]
	v_mov_b64_e32 v[74:75], v[2:3]
	v_mov_b64_e32 v[76:77], v[2:3]
	v_mov_b64_e32 v[78:79], v[2:3]
	v_mov_b64_e32 v[80:81], v[2:3]
	v_mov_b64_e32 v[90:91], v[2:3]
	v_mov_b64_e32 v[92:93], v[2:3]
	v_mov_b64_e32 v[94:95], v[2:3]
	v_mov_b64_e32 v[96:97], v[2:3]
	v_mov_b64_e32 v[106:107], v[2:3]
	v_mov_b64_e32 v[108:109], v[2:3]
	v_mov_b64_e32 v[110:111], v[2:3]
	v_mov_b64_e32 v[112:113], v[2:3]
	v_mov_b64_e32 v[122:123], v[2:3]
	v_mov_b64_e32 v[124:125], v[2:3]
	v_mov_b64_e32 v[126:127], v[2:3]
	v_mov_b64_e32 v[128:129], v[2:3]

; template <class Epi>
; DI void gemm_phase(PG8_LAS unsigned char* lds, const Gemm g, const StaticOrder& S, const Epi& E) {
;     ...
;     const bool has_next = S.next(ui + 1, nxt);
;     const char* nA = has_next ? (const char*)g.A + (size_t)nxt.pm * tstepA : cA; const char* nB = has_next ? (const char*)g.Bt + (size_t)nxt.pn * tstepB : cB;
;     ...
; #pragma unroll
;     for (int a = 0; a < 2; ++a)
; #pragma unroll
;       for (int b = 0; b < 2; ++b)
; #pragma unroll
;         for (int m = 0; m < 4; ++m)
; #pragma unroll
;           for (int n = 0; n < 2; ++n) acc[a][b][m][n] = (f32x4){0.f, 0.f, 0.f, 0.f};
;     cur = nxt; cA = nA; cB = nB; ++ui;
.LBB0_350:
	v_mov_b64_e32 v[2:3], 0x100
	s_ashr_i32 s13, s12, 31
	v_cmp_lt_i64_e32 vcc, s[14:15], v[2:3]
	s_lshl_b64 s[14:15], s[12:13], 19
	v_readlane_b32 s1, v255, 3
	s_add_u32 s14, s1, s14
	v_readlane_b32 s1, v255, 4
	s_addc_u32 s15, s1, s15
	s_and_b64 s[16:17], vcc, exec
	s_cselect_b32 s13, s15, s9
	s_cselect_b32 s21, s14, s8
	s_ashr_i32 s1, s0, 31
	s_lshl_b64 s[16:17], s[0:1], 19
	s_add_u32 s16, s34, s16
	s_addc_u32 s17, s35, s17
	s_and_b64 s[18:19], vcc, exec
	s_cselect_b32 s1, s17, s11
	s_cselect_b32 s22, s16, s10
	s_add_u32 s8, s8, 0x40080
	s_addc_u32 s9, s9, 0
	s_add_u32 s23, s10, 0x100
	v_mov_b32_e32 v2, 0
	s_addc_u32 s24, s11, 0
	s_mov_b32 s25, -2
	v_mov_b32_e32 v3, v2
	v_mov_b64_e32 v[4:5], v[2:3]
	v_mov_b64_e32 v[6:7], v[2:3]
	v_mov_b64_e32 v[8:9], v[2:3]
	v_mov_b64_e32 v[18:19], v[2:3]
	v_mov_b64_e32 v[20:21], v[2:3]
	v_mov_b64_e32 v[22:23], v[2:3]
	v_mov_b64_e32 v[24:25], v[2:3]
	v_mov_b64_e32 v[34:35], v[2:3]
	v_mov_b64_e32 v[36:37], v[2:3]
	v_mov_b64_e32 v[38:39], v[2:3]
	v_mov_b64_e32 v[40:41], v[2:3]
	v_mov_b64_e32 v[50:51], v[2:3]
	v_mov_b64_e32 v[52:53], v[2:3]
	v_mov_b64_e32 v[54:55], v[2:3]
	v_mov_b64_e32 v[56:57], v[2:3]
	v_mov_b64_e32 v[10:11], v[2:3]
	v_mov_b64_e32 v[12:13], v[2:3]
	v_mov_b64_e32 v[14:15], v[2:3]
	v_mov_b64_e32 v[16:17], v[2:3]
	v_mov_b64_e32 v[26:27], v[2:3]
	v_mov_b64_e32 v[28:29], v[2:3]
	v_mov_b64_e32 v[30:31], v[2:3]
	v_mov_b64_e32 v[32:33], v[2:3]
	v_mov_b64_e32 v[42:43], v[2:3]
	v_mov_b64_e32 v[44:45], v[2:3]
	v_mov_b64_e32 v[46:47], v[2:3]
	v_mov_b64_e32 v[48:49], v[2:3]
	v_mov_b64_e32 v[58:59], v[2:3]
	v_mov_b64_e32 v[60:61], v[2:3]
	v_mov_b64_e32 v[62:63], v[2:3]
	v_mov_b64_e32 v[64:65], v[2:3]
	v_mov_b64_e32 v[66:67], v[2:3]
	v_mov_b64_e32 v[68:69], v[2:3]
	v_mov_b64_e32 v[70:71], v[2:3]
	v_mov_b64_e32 v[72:73], v[2:3]
	v_mov_b64_e32 v[82:83], v[2:3]
	v_mov_b64_e32 v[84:85], v[2:3]
	v_mov_b64_e32 v[86:87], v[2:3]
	v_mov_b64_e32 v[88:89], v[2:3]
	v_mov_b64_e32 v[98:99], v[2:3]
	v_mov_b64_e32 v[100:101], v[2:3]
	v_mov_b64_e32 v[102:103], v[2:3]
	v_mov_b64_e32 v[104:105], v[2:3]
	v_mov_b64_e32 v[114:115], v[2:3]
	v_mov_b64_e32 v[116:117], v[2:3]
	v_mov_b64_e32 v[118:119], v[2:3]
	v_mov_b64_e32 v[120:121], v[2:3]
	v_mov_b64_e32 v[74:75], v[2:3]
	v_mov_b64_e32 v[76:77], v[2:3]
	v_mov_b64_e32 v[78:79], v[2:3]
	v_mov_b64_e32 v[80:81], v[2:3]
	v_mov_b64_e32 v[90:91], v[2:3]
	v_mov_b64_e32 v[92:93], v[2:3]
	v_mov_b64_e32 v[94:95], v[2:3]
	v_mov_b64_e32 v[96:97], v[2:3]
	v_mov_b64_e32 v[106:107], v[2:3]
	v_mov_b64_e32 v[108:109], v[2:3]
	v_mov_b64_e32 v[110:111], v[2:3]
	v_mov_b64_e32 v[112:113], v[2:3]
	v_mov_b64_e32 v[122:123], v[2:3]
	v_mov_b64_e32 v[124:125], v[2:3]
	v_mov_b64_e32 v[126:127], v[2:3]
	v_mov_b64_e32 v[128:129], v[2:3]

; template <class Epi>
; DI void gemm_phase(PG8_LAS unsigned char* lds, const Gemm g, const StaticOrder& S, const Epi& E) {
;     ...
;     const bool has_next = S.next(ui + 1, nxt);
;     const char* nA = has_next ? (const char*)g.A + (size_t)nxt.pm * tstepA : cA; const char* nB = has_next ? (const char*)g.Bt + (size_t)nxt.pn * tstepB : cB;
;     ...
; #pragma unroll
;     for (int a = 0; a < 2; ++a)
; #pragma unroll
;       for (int b = 0; b < 2; ++b)
; #pragma unroll
;         for (int m = 0; m < 4; ++m)
; #pragma unroll
;           for (int n = 0; n < 2; ++n) acc[a][b][m][n] = (f32x4){0.f, 0.f, 0.f, 0.f};
;     cur = nxt; cA = nA; cB = nB; ++ui;
.LBB0_478:
	v_mov_b64_e32 v[2:3], 0x1200
	s_ashr_i32 s13, s12, 31
	v_cmp_lt_i64_e32 vcc, s[14:15], v[2:3]
	s_lshl_b64 s[14:15], s[12:13], 19
	s_add_u32 s14, s36, s14
	s_addc_u32 s15, s37, s15
	s_and_b64 s[16:17], vcc, exec
	s_cselect_b32 s13, s15, s9
	s_cselect_b32 s21, s14, s8
	s_ashr_i32 s1, s0, 31
	s_lshl_b64 s[16:17], s[0:1], 19
	s_add_u32 s16, s69, s16
	s_addc_u32 s17, s93, s17
	s_and_b64 s[18:19], vcc, exec
	s_cselect_b32 s1, s17, s11
	s_cselect_b32 s22, s16, s10
	s_add_u32 s8, s8, 0x40080
	s_addc_u32 s9, s9, 0
	s_add_u32 s23, s10, 0x100
	v_mov_b32_e32 v2, 0
	s_addc_u32 s24, s11, 0
	s_mov_b32 s25, -2
	v_mov_b32_e32 v3, v2
	v_mov_b64_e32 v[4:5], v[2:3]
	v_mov_b64_e32 v[6:7], v[2:3]
	v_mov_b64_e32 v[8:9], v[2:3]
	v_mov_b64_e32 v[18:19], v[2:3]
	v_mov_b64_e32 v[20:21], v[2:3]
	v_mov_b64_e32 v[22:23], v[2:3]
	v_mov_b64_e32 v[24:25], v[2:3]
	v_mov_b64_e32 v[34:35], v[2:3]
	v_mov_b64_e32 v[36:37], v[2:3]
	v_mov_b64_e32 v[38:39], v[2:3]
	v_mov_b64_e32 v[40:41], v[2:3]
	v_mov_b64_e32 v[50:51], v[2:3]
	v_mov_b64_e32 v[52:53], v[2:3]
	v_mov_b64_e32 v[54:55], v[2:3]
	v_mov_b64_e32 v[56:57], v[2:3]
	v_mov_b64_e32 v[10:11], v[2:3]
	v_mov_b64_e32 v[12:13], v[2:3]
	v_mov_b64_e32 v[14:15], v[2:3]
	v_mov_b64_e32 v[16:17], v[2:3]
	v_mov_b64_e32 v[26:27], v[2:3]
	v_mov_b64_e32 v[28:29], v[2:3]
	v_mov_b64_e32 v[30:31], v[2:3]
	v_mov_b64_e32 v[32:33], v[2:3]
	v_mov_b64_e32 v[42:43], v[2:3]
	v_mov_b64_e32 v[44:45], v[2:3]
	v_mov_b64_e32 v[46:47], v[2:3]
	v_mov_b64_e32 v[48:49], v[2:3]
	v_mov_b64_e32 v[58:59], v[2:3]
	v_mov_b64_e32 v[60:61], v[2:3]
	v_mov_b64_e32 v[62:63], v[2:3]
	v_mov_b64_e32 v[64:65], v[2:3]
	v_mov_b64_e32 v[66:67], v[2:3]
	v_mov_b64_e32 v[68:69], v[2:3]
	v_mov_b64_e32 v[70:71], v[2:3]
	v_mov_b64_e32 v[72:73], v[2:3]
	v_mov_b64_e32 v[82:83], v[2:3]
	v_mov_b64_e32 v[84:85], v[2:3]
	v_mov_b64_e32 v[86:87], v[2:3]
	v_mov_b64_e32 v[88:89], v[2:3]
	v_mov_b64_e32 v[98:99], v[2:3]
	v_mov_b64_e32 v[100:101], v[2:3]
	v_mov_b64_e32 v[102:103], v[2:3]
	v_mov_b64_e32 v[104:105], v[2:3]
	v_mov_b64_e32 v[114:115], v[2:3]
	v_mov_b64_e32 v[116:117], v[2:3]
	v_mov_b64_e32 v[118:119], v[2:3]
	v_mov_b64_e32 v[120:121], v[2:3]
	v_mov_b64_e32 v[74:75], v[2:3]
	v_mov_b64_e32 v[76:77], v[2:3]
	v_mov_b64_e32 v[78:79], v[2:3]
	v_mov_b64_e32 v[80:81], v[2:3]
	v_mov_b64_e32 v[90:91], v[2:3]
	v_mov_b64_e32 v[92:93], v[2:3]
	v_mov_b64_e32 v[94:95], v[2:3]
	v_mov_b64_e32 v[96:97], v[2:3]
	v_mov_b64_e32 v[106:107], v[2:3]
	v_mov_b64_e32 v[108:109], v[2:3]
	v_mov_b64_e32 v[110:111], v[2:3]
	v_mov_b64_e32 v[112:113], v[2:3]
	v_mov_b64_e32 v[122:123], v[2:3]
	v_mov_b64_e32 v[124:125], v[2:3]
	v_mov_b64_e32 v[126:127], v[2:3]
	v_mov_b64_e32 v[128:129], v[2:3]

; template <class Epi>
; DI void gemm_phase(PG8_LAS unsigned char* lds, const Gemm g, const StaticOrder& S, const Epi& E) {
;     ...
;     const bool has_next = S.next(ui + 1, nxt);
;     const char* nA = has_next ? (const char*)g.A + (size_t)nxt.pm * tstepA : cA; const char* nB = has_next ? (const char*)g.Bt + (size_t)nxt.pn * tstepB : cB;
;     ...
; #pragma unroll
;     for (int a = 0; a < 2; ++a)
; #pragma unroll
;       for (int b = 0; b < 2; ++b)
; #pragma unroll
;         for (int m = 0; m < 4; ++m)
; #pragma unroll
;           for (int n = 0; n < 2; ++n) acc[a][b][m][n] = (f32x4){0.f, 0.f, 0.f, 0.f};
;     cur = nxt; cA = nA; cB = nB; ++ui;
.LBB0_598:
	s_ashr_i32 s97, s96, 31
	v_cmp_lt_i64_e32 vcc, s[14:15], v[146:147]
	s_lshl_b64 s[14:15], s[96:97], 19
	s_add_u32 s88, s36, s14
	s_addc_u32 s89, s37, s15
	s_and_b64 s[14:15], vcc, exec
	s_cselect_b32 s17, s89, s11
	s_cselect_b32 s20, s88, s10
	s_ashr_i32 s1, s0, 31
	s_lshl_b64 s[14:15], s[0:1], 19
	s_add_u32 s18, s90, s14
	s_addc_u32 s19, s73, s15
	s_and_b64 s[14:15], vcc, exec
	s_cselect_b32 s1, s19, s13
	s_cselect_b32 s21, s18, s12
	s_add_u32 s10, s10, 0x40080
	s_addc_u32 s11, s11, 0
	s_add_u32 s22, s12, 0x100
	v_mov_b32_e32 v2, 0
	s_addc_u32 s23, s13, 0
	s_mov_b32 s24, -2
	v_mov_b32_e32 v3, v2
	v_mov_b64_e32 v[4:5], v[2:3]
	v_mov_b64_e32 v[6:7], v[2:3]
	v_mov_b64_e32 v[8:9], v[2:3]
	v_mov_b64_e32 v[18:19], v[2:3]
	v_mov_b64_e32 v[20:21], v[2:3]
	v_mov_b64_e32 v[22:23], v[2:3]
	v_mov_b64_e32 v[24:25], v[2:3]
	v_mov_b64_e32 v[34:35], v[2:3]
	v_mov_b64_e32 v[36:37], v[2:3]
	v_mov_b64_e32 v[38:39], v[2:3]
	v_mov_b64_e32 v[40:41], v[2:3]
	v_mov_b64_e32 v[50:51], v[2:3]
	v_mov_b64_e32 v[52:53], v[2:3]
	v_mov_b64_e32 v[54:55], v[2:3]
	v_mov_b64_e32 v[56:57], v[2:3]
	v_mov_b64_e32 v[10:11], v[2:3]
	v_mov_b64_e32 v[12:13], v[2:3]
	v_mov_b64_e32 v[14:15], v[2:3]
	v_mov_b64_e32 v[16:17], v[2:3]
	v_mov_b64_e32 v[26:27], v[2:3]
	v_mov_b64_e32 v[28:29], v[2:3]
	v_mov_b64_e32 v[30:31], v[2:3]
	v_mov_b64_e32 v[32:33], v[2:3]
	v_mov_b64_e32 v[42:43], v[2:3]
	v_mov_b64_e32 v[44:45], v[2:3]
	v_mov_b64_e32 v[46:47], v[2:3]
	v_mov_b64_e32 v[48:49], v[2:3]
	v_mov_b64_e32 v[58:59], v[2:3]
	v_mov_b64_e32 v[60:61], v[2:3]
	v_mov_b64_e32 v[62:63], v[2:3]
	v_mov_b64_e32 v[64:65], v[2:3]
	v_mov_b64_e32 v[66:67], v[2:3]
	v_mov_b64_e32 v[68:69], v[2:3]
	v_mov_b64_e32 v[70:71], v[2:3]
	v_mov_b64_e32 v[72:73], v[2:3]
	v_mov_b64_e32 v[82:83], v[2:3]
	v_mov_b64_e32 v[84:85], v[2:3]
	v_mov_b64_e32 v[86:87], v[2:3]
	v_mov_b64_e32 v[88:89], v[2:3]
	v_mov_b64_e32 v[98:99], v[2:3]
	v_mov_b64_e32 v[100:101], v[2:3]
	v_mov_b64_e32 v[102:103], v[2:3]
	v_mov_b64_e32 v[104:105], v[2:3]
	v_mov_b64_e32 v[114:115], v[2:3]
	v_mov_b64_e32 v[116:117], v[2:3]
	v_mov_b64_e32 v[118:119], v[2:3]
	v_mov_b64_e32 v[120:121], v[2:3]
	v_mov_b64_e32 v[74:75], v[2:3]
	v_mov_b64_e32 v[76:77], v[2:3]
	v_mov_b64_e32 v[78:79], v[2:3]
	v_mov_b64_e32 v[80:81], v[2:3]
	v_mov_b64_e32 v[90:91], v[2:3]
	v_mov_b64_e32 v[92:93], v[2:3]
	v_mov_b64_e32 v[94:95], v[2:3]
	v_mov_b64_e32 v[96:97], v[2:3]
	v_mov_b64_e32 v[106:107], v[2:3]
	v_mov_b64_e32 v[108:109], v[2:3]
	v_mov_b64_e32 v[110:111], v[2:3]
	v_mov_b64_e32 v[112:113], v[2:3]
	v_mov_b64_e32 v[122:123], v[2:3]
	v_mov_b64_e32 v[124:125], v[2:3]
	v_mov_b64_e32 v[126:127], v[2:3]
	v_mov_b64_e32 v[128:129], v[2:3]

; #define LAS3 __attribute__((address_space(3)))
; template <int MK> ...
;   f32x16 s0 = qk_tile(k0, L, q0, q1, q2, q3, init);
;   f32x16 s1 = qk_tile(k1, L, q0, q1, q2, q3, init);
;   if (MK == 2) {
; #pragma unroll
;     for (int v = 0; v < 16; ++v) { s0[v] += b0[(v & 3) + 8 * (v >> 2)]; s1[v] += b1[(v & 3) + 8 * (v >> 2)]; }
;   }
;   if (MK == 1 && kb1 != 0x7fffffff) {
;     const int lo = max(0, sq - 128), hi = min(2047, sq + 128);
;     const int L0 = lo - kb0 - 4 * h, H0 = hi - kb0 - 4 * h, L1 = lo - kb1 - 4 * h, H1 = hi - kb1 - 4 * h;
; #pragma unroll
;     for (int v = 0; v < 16; ++v) {
;       const int cv = (v & 3) + 8 * (v >> 2);
;       s0[v] = (cv >= L0 && cv <= H0) ? s0[v] : -1e30f;
;       s1[v] = (cv >= L1 && cv <= H1) ? s1[v] : -1e30f;
;     }
;   }
; #pragma unroll
;   for (int v = 0; v < 16; ++v) s0[v] = __builtin_amdgcn_exp2f(s0[v]);
;   const float a0 = (s0[0] + s0[1]) + (s0[2] + s0[3]), a1 = (s0[4] + s0[5]) + (s0[6] + s0[7]);
;   const float a2 = (s0[8] + s0[9]) + (s0[10] + s0[11]), a3 = (s0[12] + s0[13]) + (s0[14] + s0[15]);
;   pv_tile(v0, L, s0, st.o0, st.o1);
; #pragma unroll
;   for (int v = 0; v < 16; ++v) s1[v] = __builtin_amdgcn_exp2f(s1[v]);
; template <int MODE>
; DI void attn_seq(const Params& p, int layer, char* smem, const int tid, const int nitems, bf16_t* ob, const int ostride) {
;     ...
;         const int rrA = d.a0 + 2 * (u - 2), rrB = rrA + 1;
;         const bool inA = (rrA >= wr_lo) && (rrA <= wr_hi), inB = (rrB >= wr_lo) && (rrB <= wr_hi) && (rrB <= d.a1);
;         if (inA || inB) {
;           const int rs_q = clampi(rq - 4, 0, 24);
;           const bool okA = (rrA >= rs_q) && (rrA < rs_q + 8), okB = (rrB >= rs_q) && (rrB < rs_q + 8) && (rrB <= d.a1);
;           LAS3 const float* bA = (okA ? (tab + TAB_HEAD0 + (hq - hq_first) * TAB_HSTR + (rrA - rq + 7) * 31) : (tab + TAB_NEG + 32)) + colbase;
;           LAS3 const float* bB = (okB ? (tab + TAB_HEAD0 + (hq - hq_first) * TAB_HSTR + (rrB - rq + 7) * 31) : (tab + TAB_NEG + 32)) + colbase;
;           attn_chunk<2>(Kb, Kb + 64 * 128, Vb, Vb + 64 * 128, L, q0f, q1f, q2f, q3f, st, st.cinit, h, 0, 0, 0, bA, bB);
.Lm1_compute:
	v_add_u32_e32 v66, s22, v183
	ds_read_b128 v[82:85], v66
	ds_read_b128 v[100:103], v66 offset:8192
	v_add_u32_e32 v86, s22, v184
	v_add_u32_e32 v87, s22, v185
	v_cmp_ge_i32_e64 s[6:7], s23, v135
	v_cmp_lt_i32_e64 s[8:9], s23, v137
	s_and_b64 s[6:7], s[6:7], s[8:9]
	s_movk_i32 s8, 0x7c
	v_cmp_ge_i32_e32 vcc, s24, v135
	s_waitcnt lgkmcnt(0)
	v_mfma_f32_32x32x16_bf16 v[66:81], v[82:85], v[128:131], v[34:49]
	ds_read_b128 v[82:85], v86
	ds_read_b128 v[104:107], v86 offset:8192
	v_add_u32_e32 v86, s22, v186
	v_cmp_lt_i32_e64 s[0:1], s24, v137
	v_readlane_b32 s9, v255, 23
	s_and_b64 vcc, vcc, s[0:1]
	ds_read_b128 v[108:111], v87 offset:8192
	s_waitcnt lgkmcnt(0)
	v_mfma_f32_32x32x16_bf16 v[66:81], v[82:85], v[124:127], v[66:81]
	ds_read_b128 v[82:85], v87
	s_waitcnt lgkmcnt(0)
	v_mfma_f32_32x32x16_bf16 v[66:81], v[82:85], v[120:123], v[66:81]
	ds_read_b128 v[82:85], v86
	ds_read_b128 v[112:115], v86 offset:8192
	s_waitcnt lgkmcnt(0)
	v_mfma_f32_32x32x16_bf16 v[66:81], v[82:85], v[116:119], v[66:81]
	v_sub_u32_e32 v82, s24, v99
	v_mul_lo_u32 v98, v82, s8
	v_add_u32_e32 v98, s20, v98
	v_add_u32_e32 v98, 0x364, v98
	v_mfma_f32_32x32x16_bf16 v[82:97], v[100:103], v[128:131], v[34:49]
	v_add_u32_e32 v101, 0x7c, v98
	v_mov_b32_e32 v100, s9
	v_cndmask_b32_e32 v98, v100, v98, vcc
	s_and_b64 vcc, s[6:7], s[88:89]
	v_mfma_f32_32x32x16_bf16 v[82:97], v[104:107], v[124:127], v[82:97]
	v_add_u32_e32 v98, v98, v168
	v_cndmask_b32_e32 v100, v100, v101, vcc
	v_add_u32_e32 v191, v100, v168
	ds_read2_b32 v[100:101], v98 offset0:15 offset1:16
	ds_read2_b32 v[102:103], v98 offset0:17 offset1:18
	ds_read2_b32 v[104:105], v98 offset0:23 offset1:24
	ds_read2_b32 v[106:107], v98 offset0:25 offset1:26
	s_waitcnt lgkmcnt(0)
	v_add_f32_e32 v102, v68, v102
	v_mfma_f32_32x32x16_bf16 v[82:97], v[108:111], v[120:123], v[82:97]
	ds_read2_b32 v[108:109], v191 offset0:15 offset1:16
	ds_read2_b32 v[110:111], v191 offset0:17 offset1:18
	ds_read2_b32 v[192:193], v191 offset0:23 offset1:24
	ds_read2_b32 v[194:195], v191 offset0:25 offset1:26
	v_add_f32_e32 v100, v66, v100
	v_add_f32_e32 v101, v67, v101
	v_add_f32_e32 v103, v69, v103
	v_add_f32_e32 v104, v70, v104
	v_add_f32_e32 v105, v71, v105
	v_add_f32_e32 v106, v72, v106
	v_mfma_f32_32x32x16_bf16 v[82:97], v[112:115], v[116:119], v[82:97]
	v_add_f32_e32 v107, v73, v107
	v_exp_f32_e32 v226, v100
	v_exp_f32_e32 v228, v101
	v_exp_f32_e32 v230, v102
	v_exp_f32_e32 v232, v103
	v_exp_f32_e32 v234, v104
	v_exp_f32_e32 v236, v105
	s_waitcnt lgkmcnt(0)
	s_nop 3
	v_add_f32_e32 v108, v82, v108
	v_add_f32_e32 v109, v83, v109
	ds_read2_b32 v[66:67], v98 offset0:31 offset1:32
	ds_read2_b32 v[68:69], v191 offset0:31 offset1:32
	ds_read2_b32 v[70:71], v98 offset0:33 offset1:34
	ds_read2_b32 v[72:73], v98 offset0:39 offset1:40
	ds_read2_b32 v[82:83], v98 offset0:41 offset1:42
	v_add_f32_e32 v110, v84, v110
	v_add_f32_e32 v111, v85, v111
	v_add_f32_e32 v196, v86, v192
	v_add_f32_e32 v213, v87, v193
	v_add_f32_e32 v221, v88, v194
	v_add_f32_e32 v225, v89, v195
	ds_read2_b32 v[84:85], v191 offset0:33 offset1:34
	ds_read2_b32 v[86:87], v191 offset0:39 offset1:40
	ds_read2_b32 v[88:89], v191 offset0:41 offset1:42
	s_waitcnt lgkmcnt(0)
	v_add_f32_e32 v191, v91, v69
	v_add_f32_e32 v69, v77, v71
	v_add_f32_e32 v71, v79, v73
	v_add_f32_e32 v98, v90, v68
	v_add_f32_e32 v68, v76, v70
	v_exp_f32_e32 v252, v71
	v_add_u32_e32 v71, s22, v188
	v_exp_f32_e32 v246, v68
	v_exp_f32_e32 v248, v69
	s_nop 0
	ds_read_b64_tr_b16 v[68:69], v71 offset:16384
	v_add_f32_e32 v70, v78, v72
	v_add_f32_e32 v72, v80, v82
	v_add_f32_e32 v73, v81, v83
	v_exp_f32_e32 v238, v106
	v_exp_f32_e32 v240, v107
	v_exp_f32_e32 v220, v72
	v_add_u32_e32 v72, s22, v189
	v_exp_f32_e32 v212, v73
	v_add_u32_e32 v73, s22, v190
	ds_read_b64_tr_b16 v[100:101], v72 offset:16384
	ds_read_b64_tr_b16 v[102:103], v73 offset:16384
	v_add_f32_e32 v66, v74, v66
	v_add_f32_e32 v67, v75, v67
	v_exp_f32_e32 v250, v70
	v_add_u32_e32 v70, s22, v187
	v_cvt_pk_bf16_f32 v192, v226, v228
	v_cvt_pk_bf16_f32 v193, v230, v232
	v_cvt_pk_bf16_f32 v194, v234, v236
	v_cvt_pk_bf16_f32 v195, v238, v240
	v_add_f32_e32 v247, v92, v84
	v_add_f32_e32 v249, v93, v85
	v_add_f32_e32 v251, v94, v86
	v_add_f32_e32 v253, v95, v87
	v_add_f32_e32 v215, v96, v88
	v_add_f32_e32 v219, v97, v89
	v_exp_f32_e32 v242, v66
	v_exp_f32_e32 v244, v67
	v_exp_f32_e32 v227, v108
	v_exp_f32_e32 v229, v109
	v_exp_f32_e32 v231, v110
	v_exp_f32_e32 v233, v111
	ds_read_b64_tr_b16 v[66:67], v70 offset:16384
	ds_read_b64_tr_b16 v[104:105], v70 offset:18432
	ds_read_b64_tr_b16 v[108:109], v70 offset:24576
	ds_read_b64_tr_b16 v[112:113], v70 offset:26624
	ds_read_b64_tr_b16 v[106:107], v71 offset:18432
	ds_read_b64_tr_b16 v[110:111], v71 offset:24576
	ds_read_b64_tr_b16 v[114:115], v71 offset:26624
	s_waitcnt lgkmcnt(6)
; template <int MK> ...
;     ...
;   for (int v = 0; v < 16; ++v) s0[v] = __builtin_amdgcn_exp2f(s0[v]);
;   const float a0 = (s0[0] + s0[1]) + (s0[2] + s0[3]), a1 = (s0[4] + s0[5]) + (s0[6] + s0[7]);
;   const float a2 = (s0[8] + s0[9]) + (s0[10] + s0[11]), a3 = (s0[12] + s0[13]) + (s0[14] + s0[15]);
;   pv_tile(v0, L, s0, st.o0, st.o1);
; #pragma unroll
;   for (int v = 0; v < 16; ++v) s1[v] = __builtin_amdgcn_exp2f(s1[v]);
;   const float a4 = (s1[0] + s1[1]) + (s1[2] + s1[3]), a5 = (s1[4] + s1[5]) + (s1[6] + s1[7]);
;   const float a6 = (s1[8] + s1[9]) + (s1[10] + s1[11]), a7 = (s1[12] + s1[13]) + (s1[14] + s1[15]);
;   pv_tile(v1, L, s1, st.o0, st.o1);
;   const float sum = ((a0 + a1) + (a2 + a3)) + ((a4 + a5) + (a6 + a7));
;   st.l += sum;
;   const float tot = sum + __shfl_xor(sum, 32);
;   if (__builtin_amdgcn_ballot_w64(tot > 256.f) != 0) {
;     const float delta = fmaxf(__builtin_amdgcn_logf(tot), 0.f);
;     const float alpha = __builtin_amdgcn_exp2f(-delta);
;     st.m += delta; st.l *= alpha;
; #pragma unroll
;     for (int v = 0; v < 16; ++v) { st.cinit[v] -= delta; st.o0[v] *= alpha; st.o1[v] *= alpha; }
;   }
	v_mfma_f32_32x32x16_bf16 v[50:65], v[66:69], v[192:195], v[50:65]
	v_exp_f32_e32 v235, v196
	ds_read_b64_tr_b16 v[196:197], v72 offset:18432
	ds_read_b64_tr_b16 v[200:201], v72 offset:24576
	ds_read_b64_tr_b16 v[204:205], v72 offset:26624
	ds_read_b64_tr_b16 v[198:199], v73 offset:18432
	ds_read_b64_tr_b16 v[202:203], v73 offset:24576
	ds_read_b64_tr_b16 v[206:207], v73 offset:26624
	v_exp_f32_e32 v237, v213
	v_exp_f32_e32 v239, v221
	v_exp_f32_e32 v241, v225
	v_exp_f32_e32 v243, v98
	v_exp_f32_e32 v245, v191
	v_mfma_f32_32x32x16_bf16 v[18:33], v[100:103], v[192:195], v[18:33]
	v_cvt_pk_bf16_f32 v100, v242, v244
	v_cvt_pk_bf16_f32 v101, v246, v248
	v_cvt_pk_bf16_f32 v102, v250, v252
	v_cvt_pk_bf16_f32 v103, v220, v212
	v_exp_f32_e32 v247, v247
	v_exp_f32_e32 v249, v249
	v_exp_f32_e32 v251, v251
	s_waitcnt lgkmcnt(8)
	v_mfma_f32_32x32x16_bf16 v[50:65], v[104:107], v[100:103], v[50:65]
	v_exp_f32_e32 v253, v253
	v_exp_f32_e32 v221, v215
	v_exp_f32_e32 v213, v219
	v_add_f32_e32 v104, v226, v228
	v_add_f32_e32 v105, v227, v229
	v_add_f32_e32 v106, v230, v232
	v_add_f32_e32 v107, v231, v233
	v_xor_b32_e32 v98, 32, v214
	v_add_f32_e32 v104, v104, v106
	v_add_f32_e32 v105, v105, v107
	s_waitcnt lgkmcnt(2)
	v_mfma_f32_32x32x16_bf16 v[18:33], v[196:199], v[100:103], v[18:33]
	v_cvt_pk_bf16_f32 v100, v227, v229
	v_cvt_pk_bf16_f32 v101, v231, v233
	v_cvt_pk_bf16_f32 v102, v235, v237
	v_cvt_pk_bf16_f32 v103, v239, v241
	v_add_f32_e64 v106, v234, v236
	v_add_f32_e64 v107, v235, v237
	v_mfma_f32_32x32x16_bf16 v[50:65], v[108:111], v[100:103], v[50:65]
	v_add_f32_e64 v108, v238, v240
	v_add_f32_e64 v109, v239, v241
	v_add_f32_e64 v110, v246, v248
	v_add_f32_e64 v111, v247, v249
	v_add_f32_e64 v106, v106, v108
	v_add_f32_e64 v107, v107, v109
	v_add_f32_e32 v108, v242, v244
	v_add_f32_e32 v109, v243, v245
	v_add_f32_e32 v104, v104, v106
	v_add_f32_e32 v105, v105, v107
	v_add_f32_e32 v108, v108, v110
	v_add_f32_e32 v109, v109, v111
	s_waitcnt lgkmcnt(1)
	v_mfma_f32_32x32x16_bf16 v[18:33], v[200:203], v[100:103], v[18:33]
	v_add_f32_e64 v100, v250, v252
	v_add_f32_e64 v101, v251, v253
	v_add_f32_e64 v102, v220, v212
	v_add_f32_e64 v103, v221, v213
	v_add_f32_e64 v110, v100, v102
	v_add_f32_e64 v111, v101, v103
	v_cvt_pk_bf16_f32 v100, v243, v245
	v_add_f32_e32 v106, v108, v110
	v_add_f32_e32 v107, v109, v111
	v_cvt_pk_bf16_f32 v101, v247, v249
	v_add_f32_e32 v104, v104, v106
	v_add_f32_e32 v105, v105, v107
	v_cvt_pk_bf16_f32 v102, v251, v253
	v_add_f32_e32 v104, v104, v105
	v_and_b32_e32 v105, 64, v214
	v_add_u32_e32 v105, 64, v105
	v_cmp_lt_i32_e32 vcc, v98, v105
	v_cvt_pk_bf16_f32 v103, v221, v213
	s_nop 0
	v_cndmask_b32_e32 v98, v214, v98, vcc
	v_mfma_f32_32x32x16_bf16 v[50:65], v[112:115], v[100:103], v[50:65]
	v_lshlrev_b32_e32 v98, 2, v98
	ds_bpermute_b32 v105, v98, v104
	v_add_f32_e32 v181, v181, v104
	s_waitcnt lgkmcnt(1)
	v_mfma_f32_32x32x16_bf16 v[18:33], v[204:207], v[100:103], v[18:33]
	s_waitcnt lgkmcnt(0)
	v_add_f32_e32 v100, v104, v105
	v_cmp_lt_f32_e32 vcc, s68, v100
	s_cbranch_vccz .Lm1_cdone
	v_log_f32_e32 v100, v100
	s_nop 0
	v_max_f32_e32 v100, 0, v100
	v_exp_f32_e64 v192, -v100
	v_add_f32_e32 v182, v182, v100
	v_sub_f32_e32 v49, v49, v100
	v_sub_f32_e32 v48, v48, v100
	v_sub_f32_e32 v47, v47, v100
	v_sub_f32_e32 v46, v46, v100
	v_sub_f32_e32 v45, v45, v100
	v_mul_f32_e32 v181, v181, v192
	v_sub_f32_e32 v44, v44, v100
	v_sub_f32_e32 v43, v43, v100
	v_sub_f32_e32 v42, v42, v100
	v_sub_f32_e32 v41, v41, v100
	v_sub_f32_e32 v40, v40, v100
	v_sub_f32_e32 v39, v39, v100
	v_sub_f32_e32 v38, v38, v100
	v_sub_f32_e32 v37, v37, v100
	v_sub_f32_e32 v36, v36, v100
	v_sub_f32_e32 v35, v35, v100
	v_sub_f32_e32 v34, v34, v100
	v_pk_mul_f32 v[64:65], v[64:65], v[192:193] op_sel_hi:[1,0]
	v_pk_mul_f32 v[62:63], v[62:63], v[192:193] op_sel_hi:[1,0]
	v_pk_mul_f32 v[60:61], v[60:61], v[192:193] op_sel_hi:[1,0]
	v_pk_mul_f32 v[58:59], v[58:59], v[192:193] op_sel_hi:[1,0]
	v_pk_mul_f32 v[56:57], v[56:57], v[192:193] op_sel_hi:[1,0]
	v_pk_mul_f32 v[54:55], v[54:55], v[192:193] op_sel_hi:[1,0]
	v_pk_mul_f32 v[52:53], v[52:53], v[192:193] op_sel_hi:[1,0]
	v_pk_mul_f32 v[50:51], v[50:51], v[192:193] op_sel_hi:[1,0]
	v_pk_mul_f32 v[32:33], v[32:33], v[192:193] op_sel_hi:[1,0]
	v_pk_mul_f32 v[30:31], v[30:31], v[192:193] op_sel_hi:[1,0]
	v_pk_mul_f32 v[28:29], v[28:29], v[192:193] op_sel_hi:[1,0]
	v_pk_mul_f32 v[26:27], v[26:27], v[192:193] op_sel_hi:[1,0]
	v_pk_mul_f32 v[24:25], v[24:25], v[192:193] op_sel_hi:[1,0]
	v_pk_mul_f32 v[22:23], v[22:23], v[192:193] op_sel_hi:[1,0]
	v_pk_mul_f32 v[20:21], v[20:21], v[192:193] op_sel_hi:[1,0]
	v_pk_mul_f32 v[18:19], v[18:19], v[192:193] op_sel_hi:[1,0]
